# hyena unit start in both hyena layers: filter halo loads overlapped with the row loads (narrowed halo loads, wait moved to the consumers)
# baseline (speedup 1.0000x reference)
.LBB0_1431:
	s_or_b64 exec, exec, s[8:9]
	v_cmp_gt_u32_e32 vcc, s42, v116
	v_mov_b32_e32 v30, 0
	s_and_saveexec_b64 s[8:9], vcc
	s_cbranch_execz .LBB0_1433
	v_ashrrev_i32_e32 v3, 31, v114
	v_mov_b32_e32 v2, v114
	v_lshl_add_u64 v[2:3], v[2:3], 1, s[16:17]
	global_load_dwordx2 v[30:31], v[2:3], off offset:16

.LBB0_1437:
	s_or_b64 exec, exec, s[10:11]
	v_cmp_lt_u32_e32 vcc, s43, v116
	v_mov_b32_e32 v44, 0
	s_and_saveexec_b64 s[10:11], vcc
	s_cbranch_execz .LBB0_1439
	v_ashrrev_i32_e32 v49, 31, v48
	v_lshl_add_u64 v[2:3], v[48:49], 1, s[16:17]
	global_load_dwordx2 v[44:45], v[2:3], off offset:16

.LBB0_1446:
	s_or_b64 exec, exec, s[10:11]
	v_add_u32_e32 v46, 0x1000, v116
	v_ashrrev_i32_e32 v47, 31, v46
	v_lshrrev_b32_e32 v2, 21, v47
	v_add_u32_e32 v2, v46, v2
	v_and_b32_e32 v2, 0xfffff800, v2
	s_movk_i32 s0, 0x600
	v_sub_u32_e32 v78, v46, v2
	v_cmp_gt_i32_e64 s[14:15], s0, v139
	v_mov_b32_e32 v66, 0
	v_mov_b32_e32 v65, 0
	v_mov_b32_e32 v35, 0
	v_mov_b32_e32 v34, 0
	v_mov_b32_e32 v33, 0
	v_mov_b32_e32 v32, 0
	s_and_saveexec_b64 s[10:11], s[14:15]
	s_cbranch_execz .LBB0_1452
	v_lshl_add_u64 v[2:3], v[46:47], 1, s[24:25]
	global_load_dwordx4 v[32:35], v[2:3], off
	v_cmp_lt_i32_e64 s[0:1], 0, v78
	v_mov_b32_e32 v66, 0
	v_mov_b32_e32 v65, 0
	s_and_saveexec_b64 s[12:13], s[0:1]
	s_cbranch_execz .LBB0_1449
	global_load_ushort v65, v[2:3], off offset:-2

.LBB0_1489:
	s_waitcnt vmcnt(0)
	v_perm_b32 v23, v41, v42, s65
	v_perm_b32 v24, v42, v43, s65
	v_perm_b32 v25, v43, v44, s65
	v_perm_b32 v22, v40, v41, s65
	v_pk_mov_b32 v[72:73], v[42:43], v[44:45] op_sel:[1,0]
	v_pk_mov_b32 v[70:71], v[40:41], v[42:43] op_sel:[1,0]
	v_perm_b32 v77, v44, v45, s65
	v_mov_b32_e32 v74, v23
	v_mov_b32_e32 v75, v24
	v_mov_b32_e32 v76, v25
	ds_write_b128 v125, v[40:43] offset:8192
	ds_write_b128 v125, v[22:25] offset:16416
	ds_write_b128 v125, v[70:73] offset:24640
	ds_write_b128 v125, v[74:77] offset:32864

.LBB0_1503:
	s_waitcnt vmcnt(0)
	v_perm_b32 v71, v23, v24, s65
	v_perm_b32 v72, v24, v25, s65
	v_perm_b32 v73, v25, v30, s65
	v_perm_b32 v70, v22, v23, s65
	v_pk_mov_b32 v[76:77], v[24:25], v[30:31] op_sel:[1,0]
	v_pk_mov_b32 v[74:75], v[22:23], v[24:25] op_sel:[1,0]
	v_perm_b32 v83, v30, v31, s65
	v_mov_b32_e32 v80, v71
	v_mov_b32_e32 v81, v72
	v_mov_b32_e32 v82, v73
	ds_write_b128 v125, v[22:25]
	ds_write_b128 v125, v[70:73] offset:8224
	ds_write_b128 v125, v[74:77] offset:16448
	ds_write_b128 v125, v[80:83] offset:24672
	s_or_b64 exec, exec, s[0:1]
	s_and_saveexec_b64 s[0:1], s[8:9]
	s_cbranch_execnz .LBB0_1489
	s_branch .LBB0_1490
